# GEMM K-loops: iteration counter and last-iterations test moved into the MFMA shadow of the last stage; one untaken branch + back edge after the last MFMA
# baseline (speedup 1.0000x reference)
; #define PG8_STAGE(bufoff, gbase, voff) do { _Pragma("unroll") for (int _i = 0; _i < 2; ++_i) \
;         __builtin_amdgcn_global_load_lds((const unsigned*)((const char*)(gbase) + (voff)[_i]), (PG8_LAS unsigned*)(lds + (bufoff) + ldsw + _i * 8192), 16, 0, 0); } while (0)
; #define PG8_LDA(dst, b, h) do { _Pragma("unroll") for (int m = 0; m < 4; ++m) _Pragma("unroll") for (int k = 0; k < 2; ++k) dst[m][k] = *(const PG8_LAS bf16x8*)(lds + PG8_SA(b, h) + aoff + m * 2048 + k * 1024); } while (0)
; #define PG8_LDB(dst, b, h) do { _Pragma("unroll") for (int n = 0; n < 2; ++n) _Pragma("unroll") for (int k = 0; k < 2; ++k) dst[n][k] = *(const PG8_LAS bf16x8*)(lds + PG8_SB(b, h) + boff + n * 2048 + k * 1024); } while (0)
; #define PG8_MMA(ai, bj, At, Bt) do { __builtin_amdgcn_s_setprio(1); _Pragma("unroll") for (int m = 0; m < 4; ++m) _Pragma("unroll") for (int n = 0; n < 2; ++n) _Pragma("unroll") for (int k = 0; k < 2; ++k) \
;         acc[ai][bj][m][n] = __builtin_amdgcn_mfma_f32_16x16x32_bf16(Bt[n][k], At[m][k], acc[ai][bj][m][n], 0, 0, 0); __builtin_amdgcn_s_setprio(0); } while (0)
; #define PG8_WAIT_V(n) asm volatile("s_waitcnt vmcnt(" #n ")" ::: "memory")
; #define PG8_WAIT_L(n) asm volatile("s_waitcnt lgkmcnt(" #n ")" ::: "memory")
; #define PG8_BAR __builtin_amdgcn_s_barrier()
; #define PG8_SCHED __builtin_amdgcn_sched_barrier(0)
; template <class Epi, class Sched, bool ALIGN_EPI = false, bool SP2 = false>
; __device__ __forceinline__ void gemm_phase(PG8_LAS unsigned char* lds, const Gemm g, const Sched& S, const Epi& E) {
;     ...
;             PG8_LDB(B0, 0, 0); PG8_LDB(B1, 0, 1); PG8_SCHED; PG8_LDA(At, 0, 0); PG8_STAGE(PG8_SA(1, 1), a1 + hstep, voffA);
;             PG8_WAIT_V(8); PG8_WAIT_L(0); PG8_BAR; PG8_MMA(0, 0, At, B0); PG8_MMA(0, 1, At, B1); PG8_BAR; PG8_SCHED;
;             PG8_LDA(At, 0, 1); PG8_STAGE(PG8_SB(0, 0), b2, voffB); PG8_STAGE(PG8_SB(0, 1), b2 + hstep, voffB); PG8_STAGE(PG8_SA(0, 0), a2, voffA);
;             PG8_WAIT_V(8); PG8_WAIT_L(0); PG8_BAR; PG8_MMA(1, 0, At, B0); PG8_MMA(1, 1, At, B1); PG8_BAR; PG8_SCHED;
.Lp1_kloop0:
	s_waitcnt vmcnt(8)
	s_waitcnt lgkmcnt(0)
	s_barrier
	v_mfma_f32_16x16x32_bf16 v[0:3], v[196:199], v[128:131], v[0:3]
	ds_read_b128 v[212:215], v247 offset:16384
	v_mfma_f32_16x16x32_bf16 v[0:3], v[200:203], v[132:135], v[0:3]
	ds_read_b128 v[216:219], v248 offset:16384
	v_mfma_f32_16x16x32_bf16 v[4:7], v[208:211], v[132:135], v[4:7]
	ds_read_b128 v[220:223], v247 offset:18432
	v_mfma_f32_16x16x32_bf16 v[4:7], v[204:207], v[128:131], v[4:7]
	ds_read_b128 v[224:227], v248 offset:18432
	v_mfma_f32_16x16x32_bf16 v[12:15], v[204:207], v[136:139], v[12:15]
	s_add_i32 m0, s35, 0x0
	v_mfma_f32_16x16x32_bf16 v[12:15], v[208:211], v[140:143], v[12:15]
	global_load_lds_dwordx4 v249, s[30:31]
	v_mfma_f32_16x16x32_bf16 v[8:11], v[200:203], v[140:143], v[8:11]
	s_add_i32 m0, s35, 0x2000
	v_mfma_f32_16x16x32_bf16 v[8:11], v[196:199], v[136:139], v[8:11]
	global_load_lds_dwordx4 v250, s[30:31]
	v_mfma_f32_16x16x32_bf16 v[16:19], v[196:199], v[144:147], v[16:19]
	s_add_i32 m0, s35, 0x10000
	v_mfma_f32_16x16x32_bf16 v[16:19], v[200:203], v[148:151], v[16:19]
	global_load_lds_dwordx4 v251, s[32:33]
	v_mfma_f32_16x16x32_bf16 v[20:23], v[208:211], v[148:151], v[20:23]
	s_add_i32 m0, s35, 0x12000
	v_mfma_f32_16x16x32_bf16 v[20:23], v[204:207], v[144:147], v[20:23]
	global_load_lds_dwordx4 v252, s[32:33]
	v_mfma_f32_16x16x32_bf16 v[28:31], v[204:207], v[152:155], v[28:31]
	ds_read_b128 v[160:163], v245 offset:16384
	v_mfma_f32_16x16x32_bf16 v[28:31], v[208:211], v[156:159], v[28:31]
	ds_read_b128 v[164:167], v246 offset:16384
	v_mfma_f32_16x16x32_bf16 v[24:27], v[200:203], v[156:159], v[24:27]
	ds_read_b128 v[168:171], v245 offset:18432
	v_mfma_f32_16x16x32_bf16 v[24:27], v[196:199], v[152:155], v[24:27]
	ds_read_b128 v[172:175], v246 offset:18432
	s_waitcnt lgkmcnt(4)
	v_mfma_f32_16x16x32_bf16 v[32:35], v[212:215], v[128:131], v[32:35]
	ds_read_b128 v[176:179], v245 offset:20480
	v_mfma_f32_16x16x32_bf16 v[32:35], v[216:219], v[132:135], v[32:35]
	ds_read_b128 v[180:183], v246 offset:20480
	v_mfma_f32_16x16x32_bf16 v[36:39], v[224:227], v[132:135], v[36:39]
	ds_read_b128 v[188:191], v245 offset:22528
	v_mfma_f32_16x16x32_bf16 v[36:39], v[220:223], v[128:131], v[36:39]
	ds_read_b128 v[192:195], v246 offset:22528
	v_mfma_f32_16x16x32_bf16 v[44:47], v[220:223], v[136:139], v[44:47]
	v_mfma_f32_16x16x32_bf16 v[44:47], v[224:227], v[140:143], v[44:47]
	v_mfma_f32_16x16x32_bf16 v[40:43], v[216:219], v[140:143], v[40:43]
	v_mfma_f32_16x16x32_bf16 v[40:43], v[212:215], v[136:139], v[40:43]
	v_mfma_f32_16x16x32_bf16 v[48:51], v[212:215], v[144:147], v[48:51]
	v_mfma_f32_16x16x32_bf16 v[48:51], v[216:219], v[148:151], v[48:51]
	v_mfma_f32_16x16x32_bf16 v[52:55], v[224:227], v[148:151], v[52:55]
	v_mfma_f32_16x16x32_bf16 v[52:55], v[220:223], v[144:147], v[52:55]
	v_mfma_f32_16x16x32_bf16 v[60:63], v[220:223], v[152:155], v[60:63]
	v_mfma_f32_16x16x32_bf16 v[60:63], v[224:227], v[156:159], v[60:63]
	v_mfma_f32_16x16x32_bf16 v[56:59], v[216:219], v[156:159], v[56:59]
	v_mfma_f32_16x16x32_bf16 v[56:59], v[212:215], v[152:155], v[56:59]
	s_waitcnt vmcnt(8)
	s_waitcnt lgkmcnt(0)
	s_barrier
	v_mfma_f32_16x16x32_bf16 v[96:99], v[212:215], v[160:163], v[96:99]
	s_add_i32 m0, s35, 0x4000
	v_mfma_f32_16x16x32_bf16 v[96:99], v[216:219], v[164:167], v[96:99]
	global_load_lds_dwordx4 v249, s[56:57]
	v_mfma_f32_16x16x32_bf16 v[100:103], v[224:227], v[164:167], v[100:103]
	s_add_i32 m0, s35, 0x6000
	v_mfma_f32_16x16x32_bf16 v[100:103], v[220:223], v[160:163], v[100:103]
	global_load_lds_dwordx4 v250, s[56:57]
	v_mfma_f32_16x16x32_bf16 v[108:111], v[220:223], v[168:171], v[108:111]
	s_add_i32 m0, s35, 0x14000
	v_mfma_f32_16x16x32_bf16 v[108:111], v[224:227], v[172:175], v[108:111]
	global_load_lds_dwordx4 v251, s[58:59]
	v_mfma_f32_16x16x32_bf16 v[104:107], v[216:219], v[172:175], v[104:107]
	s_add_i32 m0, s35, 0x16000
	v_mfma_f32_16x16x32_bf16 v[104:107], v[212:215], v[168:171], v[104:107]
	global_load_lds_dwordx4 v252, s[58:59]
	v_mfma_f32_16x16x32_bf16 v[112:115], v[212:215], v[176:179], v[112:115]
	ds_read_b128 v[128:131], v245 offset:32768
	v_mfma_f32_16x16x32_bf16 v[112:115], v[216:219], v[180:183], v[112:115]
	ds_read_b128 v[132:135], v246 offset:32768
	v_mfma_f32_16x16x32_bf16 v[116:119], v[224:227], v[180:183], v[116:119]
	ds_read_b128 v[136:139], v245 offset:34816
	v_mfma_f32_16x16x32_bf16 v[116:119], v[220:223], v[176:179], v[116:119]
	ds_read_b128 v[140:143], v246 offset:34816
	v_mfma_f32_16x16x32_bf16 v[124:127], v[220:223], v[188:191], v[124:127]
	ds_read_b128 v[144:147], v245 offset:36864
	v_mfma_f32_16x16x32_bf16 v[124:127], v[224:227], v[192:195], v[124:127]
	ds_read_b128 v[148:151], v246 offset:36864
	v_mfma_f32_16x16x32_bf16 v[120:123], v[216:219], v[192:195], v[120:123]
	ds_read_b128 v[152:155], v245 offset:38912
	v_mfma_f32_16x16x32_bf16 v[120:123], v[212:215], v[188:191], v[120:123]
	ds_read_b128 v[156:159], v246 offset:38912
	v_mfma_f32_16x16x32_bf16 v[64:67], v[196:199], v[160:163], v[64:67]
	ds_read_b128 v[212:215], v247 offset:49152
	v_mfma_f32_16x16x32_bf16 v[64:67], v[200:203], v[164:167], v[64:67]
	ds_read_b128 v[216:219], v248 offset:49152
	v_mfma_f32_16x16x32_bf16 v[68:71], v[208:211], v[164:167], v[68:71]
	ds_read_b128 v[220:223], v247 offset:51200
	v_mfma_f32_16x16x32_bf16 v[68:71], v[204:207], v[160:163], v[68:71]
	ds_read_b128 v[224:227], v248 offset:51200
	v_mfma_f32_16x16x32_bf16 v[76:79], v[204:207], v[168:171], v[76:79]
	s_add_u32 s30, s30, s4
	s_addc_u32 s31, s31, s5
	s_add_u32 s56, s56, s4
	s_addc_u32 s57, s57, s5
	v_mfma_f32_16x16x32_bf16 v[76:79], v[208:211], v[172:175], v[76:79]
	s_add_u32 s32, s32, s4
	s_addc_u32 s33, s33, s5
	s_add_u32 s58, s58, s4
	s_addc_u32 s59, s59, s5
	v_mfma_f32_16x16x32_bf16 v[72:75], v[200:203], v[172:175], v[72:75]
	v_mfma_f32_16x16x32_bf16 v[72:75], v[196:199], v[168:171], v[72:75]
	v_mfma_f32_16x16x32_bf16 v[80:83], v[196:199], v[176:179], v[80:83]
	v_mfma_f32_16x16x32_bf16 v[80:83], v[200:203], v[180:183], v[80:83]
	v_mfma_f32_16x16x32_bf16 v[84:87], v[208:211], v[180:183], v[84:87]
	v_mfma_f32_16x16x32_bf16 v[84:87], v[204:207], v[176:179], v[84:87]
	v_mfma_f32_16x16x32_bf16 v[92:95], v[204:207], v[188:191], v[92:95]
	v_mfma_f32_16x16x32_bf16 v[92:95], v[208:211], v[192:195], v[92:95]
	v_mfma_f32_16x16x32_bf16 v[88:91], v[200:203], v[192:195], v[88:91]
	v_mfma_f32_16x16x32_bf16 v[88:91], v[196:199], v[188:191], v[88:91]
	s_waitcnt vmcnt(8)
	s_waitcnt lgkmcnt(0)
	s_barrier
; #define PG8_STAGE(bufoff, gbase, voff) do { _Pragma("unroll") for (int _i = 0; _i < 2; ++_i) \
;         __builtin_amdgcn_global_load_lds((const unsigned*)((const char*)(gbase) + (voff)[_i]), (PG8_LAS unsigned*)(lds + (bufoff) + ldsw + _i * 8192), 16, 0, 0); } while (0)
; #define PG8_LDA(dst, b, h) do { _Pragma("unroll") for (int m = 0; m < 4; ++m) _Pragma("unroll") for (int k = 0; k < 2; ++k) dst[m][k] = *(const PG8_LAS bf16x8*)(lds + PG8_SA(b, h) + aoff + m * 2048 + k * 1024); } while (0)
; #define PG8_LDB(dst, b, h) do { _Pragma("unroll") for (int n = 0; n < 2; ++n) _Pragma("unroll") for (int k = 0; k < 2; ++k) dst[n][k] = *(const PG8_LAS bf16x8*)(lds + PG8_SB(b, h) + boff + n * 2048 + k * 1024); } while (0)
; #define PG8_MMA(ai, bj, At, Bt) do { __builtin_amdgcn_s_setprio(1); _Pragma("unroll") for (int m = 0; m < 4; ++m) _Pragma("unroll") for (int n = 0; n < 2; ++n) _Pragma("unroll") for (int k = 0; k < 2; ++k) \
;         acc[ai][bj][m][n] = __builtin_amdgcn_mfma_f32_16x16x32_bf16(Bt[n][k], At[m][k], acc[ai][bj][m][n], 0, 0, 0); __builtin_amdgcn_s_setprio(0); } while (0)
; #define PG8_WAIT_V(n) asm volatile("s_waitcnt vmcnt(" #n ")" ::: "memory")
; #define PG8_WAIT_L(n) asm volatile("s_waitcnt lgkmcnt(" #n ")" ::: "memory")
; #define PG8_BAR __builtin_amdgcn_s_barrier()
; #define PG8_SCHED __builtin_amdgcn_sched_barrier(0)
; template <class Epi, class Sched, bool ALIGN_EPI = false, bool SP2 = false>
; __device__ __forceinline__ void gemm_phase(PG8_LAS unsigned char* lds, const Gemm g, const Sched& S, const Epi& E) {
;     ...
;             PG8_LDB(B0, 1, 0); PG8_LDB(B1, 1, 1); PG8_SCHED; PG8_LDA(At, 1, 0); PG8_STAGE(PG8_SA(0, 1), a2 + hstep, voffA);
;             PG8_WAIT_V(8); PG8_WAIT_L(0); PG8_BAR; PG8_MMA(0, 0, At, B0); PG8_MMA(0, 1, At, B1); PG8_BAR; PG8_SCHED;
;             PG8_LDA(At, 1, 1); PG8_STAGE(PG8_SB(1, 0), b3, voffB); PG8_STAGE(PG8_SB(1, 1), b3 + hstep, voffB); PG8_STAGE(PG8_SA(1, 0), a3, voffA);
;             PG8_WAIT_V(8); PG8_WAIT_L(0); PG8_BAR; PG8_MMA(1, 0, At, B0); PG8_MMA(1, 1, At, B1); PG8_BAR; PG8_SCHED;
	v_mfma_f32_16x16x32_bf16 v[32:35], v[212:215], v[128:131], v[32:35]
	ds_read_b128 v[196:199], v247 offset:32768
	v_mfma_f32_16x16x32_bf16 v[32:35], v[216:219], v[132:135], v[32:35]
	ds_read_b128 v[200:203], v248 offset:32768
	v_mfma_f32_16x16x32_bf16 v[36:39], v[224:227], v[132:135], v[36:39]
	ds_read_b128 v[204:207], v247 offset:34816
	v_mfma_f32_16x16x32_bf16 v[36:39], v[220:223], v[128:131], v[36:39]
	ds_read_b128 v[208:211], v248 offset:34816
	v_mfma_f32_16x16x32_bf16 v[44:47], v[220:223], v[136:139], v[44:47]
	s_add_i32 m0, s35, 0x8000
	v_mfma_f32_16x16x32_bf16 v[44:47], v[224:227], v[140:143], v[44:47]
	global_load_lds_dwordx4 v249, s[30:31]
	v_mfma_f32_16x16x32_bf16 v[40:43], v[216:219], v[140:143], v[40:43]
	s_add_i32 m0, s35, 0xa000
	v_mfma_f32_16x16x32_bf16 v[40:43], v[212:215], v[136:139], v[40:43]
	global_load_lds_dwordx4 v250, s[30:31]
	v_mfma_f32_16x16x32_bf16 v[48:51], v[212:215], v[144:147], v[48:51]
	s_add_i32 m0, s35, 0x1c000
	v_mfma_f32_16x16x32_bf16 v[48:51], v[216:219], v[148:151], v[48:51]
	global_load_lds_dwordx4 v251, s[58:59]
	v_mfma_f32_16x16x32_bf16 v[52:55], v[224:227], v[148:151], v[52:55]
	s_add_i32 m0, s35, 0x1e000
	v_mfma_f32_16x16x32_bf16 v[52:55], v[220:223], v[144:147], v[52:55]
	global_load_lds_dwordx4 v252, s[58:59]
	v_mfma_f32_16x16x32_bf16 v[60:63], v[220:223], v[152:155], v[60:63]
	ds_read_b128 v[160:163], v245 offset:49152
	v_mfma_f32_16x16x32_bf16 v[60:63], v[224:227], v[156:159], v[60:63]
	ds_read_b128 v[164:167], v246 offset:49152
	v_mfma_f32_16x16x32_bf16 v[56:59], v[216:219], v[156:159], v[56:59]
	ds_read_b128 v[168:171], v245 offset:51200
	v_mfma_f32_16x16x32_bf16 v[56:59], v[212:215], v[152:155], v[56:59]
	ds_read_b128 v[172:175], v246 offset:51200
	s_waitcnt lgkmcnt(4)
	v_mfma_f32_16x16x32_bf16 v[0:3], v[196:199], v[128:131], v[0:3]
	ds_read_b128 v[176:179], v245 offset:53248
	v_mfma_f32_16x16x32_bf16 v[0:3], v[200:203], v[132:135], v[0:3]
	ds_read_b128 v[180:183], v246 offset:53248
	v_mfma_f32_16x16x32_bf16 v[4:7], v[208:211], v[132:135], v[4:7]
	ds_read_b128 v[188:191], v245 offset:55296
	v_mfma_f32_16x16x32_bf16 v[4:7], v[204:207], v[128:131], v[4:7]
	ds_read_b128 v[192:195], v246 offset:55296
	v_mfma_f32_16x16x32_bf16 v[12:15], v[204:207], v[136:139], v[12:15]
	v_mfma_f32_16x16x32_bf16 v[12:15], v[208:211], v[140:143], v[12:15]
	v_mfma_f32_16x16x32_bf16 v[8:11], v[200:203], v[140:143], v[8:11]
	v_mfma_f32_16x16x32_bf16 v[8:11], v[196:199], v[136:139], v[8:11]
	v_mfma_f32_16x16x32_bf16 v[16:19], v[196:199], v[144:147], v[16:19]
	v_mfma_f32_16x16x32_bf16 v[16:19], v[200:203], v[148:151], v[16:19]
	v_mfma_f32_16x16x32_bf16 v[20:23], v[208:211], v[148:151], v[20:23]
	v_mfma_f32_16x16x32_bf16 v[20:23], v[204:207], v[144:147], v[20:23]
	v_mfma_f32_16x16x32_bf16 v[28:31], v[204:207], v[152:155], v[28:31]
	v_mfma_f32_16x16x32_bf16 v[28:31], v[208:211], v[156:159], v[28:31]
	v_mfma_f32_16x16x32_bf16 v[24:27], v[200:203], v[156:159], v[24:27]
	v_mfma_f32_16x16x32_bf16 v[24:27], v[196:199], v[152:155], v[24:27]
	s_waitcnt vmcnt(8)
	s_waitcnt lgkmcnt(0)
	s_barrier
	v_mfma_f32_16x16x32_bf16 v[64:67], v[196:199], v[160:163], v[64:67]
	s_add_i32 m0, s35, 0xc000
	v_mfma_f32_16x16x32_bf16 v[64:67], v[200:203], v[164:167], v[64:67]
	global_load_lds_dwordx4 v249, s[56:57]
	v_mfma_f32_16x16x32_bf16 v[68:71], v[208:211], v[164:167], v[68:71]
	s_add_i32 m0, s35, 0xe000
	v_mfma_f32_16x16x32_bf16 v[68:71], v[204:207], v[160:163], v[68:71]
	global_load_lds_dwordx4 v250, s[56:57]
	v_mfma_f32_16x16x32_bf16 v[76:79], v[204:207], v[168:171], v[76:79]
	s_add_i32 m0, s35, 0x18000
	v_mfma_f32_16x16x32_bf16 v[76:79], v[208:211], v[172:175], v[76:79]
	global_load_lds_dwordx4 v251, s[32:33]
	v_mfma_f32_16x16x32_bf16 v[72:75], v[200:203], v[172:175], v[72:75]
	s_add_i32 m0, s35, 0x1a000
	v_mfma_f32_16x16x32_bf16 v[72:75], v[196:199], v[168:171], v[72:75]
	global_load_lds_dwordx4 v252, s[32:33]
	v_mfma_f32_16x16x32_bf16 v[80:83], v[196:199], v[176:179], v[80:83]
	ds_read_b128 v[128:131], v245 offset:0
	v_mfma_f32_16x16x32_bf16 v[80:83], v[200:203], v[180:183], v[80:83]
	ds_read_b128 v[132:135], v246 offset:0
	v_mfma_f32_16x16x32_bf16 v[84:87], v[208:211], v[180:183], v[84:87]
	ds_read_b128 v[136:139], v245 offset:2048
	v_mfma_f32_16x16x32_bf16 v[84:87], v[204:207], v[176:179], v[84:87]
	ds_read_b128 v[140:143], v246 offset:2048
	v_mfma_f32_16x16x32_bf16 v[92:95], v[204:207], v[188:191], v[92:95]
	ds_read_b128 v[144:147], v245 offset:4096
	v_mfma_f32_16x16x32_bf16 v[92:95], v[208:211], v[192:195], v[92:95]
	ds_read_b128 v[148:151], v246 offset:4096
	v_mfma_f32_16x16x32_bf16 v[88:91], v[200:203], v[192:195], v[88:91]
	ds_read_b128 v[152:155], v245 offset:6144
	v_mfma_f32_16x16x32_bf16 v[88:91], v[196:199], v[188:191], v[88:91]
	ds_read_b128 v[156:159], v246 offset:6144
	v_mfma_f32_16x16x32_bf16 v[96:99], v[212:215], v[160:163], v[96:99]
	ds_read_b128 v[196:199], v247 offset:0
	v_mfma_f32_16x16x32_bf16 v[96:99], v[216:219], v[164:167], v[96:99]
	ds_read_b128 v[200:203], v248 offset:0
	v_mfma_f32_16x16x32_bf16 v[100:103], v[224:227], v[164:167], v[100:103]
	ds_read_b128 v[204:207], v247 offset:2048
	v_mfma_f32_16x16x32_bf16 v[100:103], v[220:223], v[160:163], v[100:103]
	ds_read_b128 v[208:211], v248 offset:2048
	v_mfma_f32_16x16x32_bf16 v[108:111], v[220:223], v[168:171], v[108:111]
	s_add_u32 s30, s30, s4
	s_addc_u32 s31, s31, s5
	s_add_u32 s56, s56, s4
	s_addc_u32 s57, s57, s5
	v_mfma_f32_16x16x32_bf16 v[108:111], v[224:227], v[172:175], v[108:111]
	s_add_u32 s32, s32, s4
	s_addc_u32 s33, s33, s5
	s_add_u32 s58, s58, s4
	s_addc_u32 s59, s59, s5
	v_mfma_f32_16x16x32_bf16 v[104:107], v[216:219], v[172:175], v[104:107]
	v_mfma_f32_16x16x32_bf16 v[104:107], v[212:215], v[168:171], v[104:107]
	v_mfma_f32_16x16x32_bf16 v[112:115], v[212:215], v[176:179], v[112:115]
	v_mfma_f32_16x16x32_bf16 v[112:115], v[216:219], v[180:183], v[112:115]
	v_mfma_f32_16x16x32_bf16 v[116:119], v[224:227], v[180:183], v[116:119]
	v_mfma_f32_16x16x32_bf16 v[116:119], v[220:223], v[176:179], v[116:119]
	v_mfma_f32_16x16x32_bf16 v[124:127], v[220:223], v[188:191], v[124:127]
	v_mfma_f32_16x16x32_bf16 v[124:127], v[224:227], v[192:195], v[124:127]
	v_mfma_f32_16x16x32_bf16 v[120:123], v[216:219], v[192:195], v[120:123]
	s_add_i32 s34, s34, -1
	s_cmp_le_u32 s34, 1
	v_mfma_f32_16x16x32_bf16 v[120:123], v[212:215], v[188:191], v[120:123]
	s_cbranch_scc1 .Lp1_rare0
	s_branch .Lp1_kloop0
; #define PG8_STAGE(bufoff, gbase, voff) do { _Pragma("unroll") for (int _i = 0; _i < 2; ++_i) \
;         __builtin_amdgcn_global_load_lds((const unsigned*)((const char*)(gbase) + (voff)[_i]), (PG8_LAS unsigned*)(lds + (bufoff) + ldsw + _i * 8192), 16, 0, 0); } while (0)
; #define PG8_LDA(dst, b, h) do { _Pragma("unroll") for (int m = 0; m < 4; ++m) _Pragma("unroll") for (int k = 0; k < 2; ++k) dst[m][k] = *(const PG8_LAS bf16x8*)(lds + PG8_SA(b, h) + aoff + m * 2048 + k * 1024); } while (0)
; #define PG8_LDB(dst, b, h) do { _Pragma("unroll") for (int n = 0; n < 2; ++n) _Pragma("unroll") for (int k = 0; k < 2; ++k) dst[n][k] = *(const PG8_LAS bf16x8*)(lds + PG8_SB(b, h) + boff + n * 2048 + k * 1024); } while (0)
; template <class Epi, class Sched, bool ALIGN_EPI = false, bool SP2 = false>
; __device__ __forceinline__ void gemm_phase(PG8_LAS unsigned char* lds, const Gemm g, const Sched& S, const Epi& E) {
;     ...
;         for (int t = 0; t < nt; t += 2) {
;             const bool last = (t == nt - 2);
;             const char* a1 = cA + (size_t)(t + 1) * kstep;
;             const char* a2 = last ? nA : cA + (size_t)(t + 2) * kstep; const char* b2 = last ? nB : cB + (size_t)(t + 2) * kstep;
;             const char* a3 = a2 + kstep; const char* b3 = b2 + kstep;
;             if (last && has_next) S.a_ready(nxt);
;             if constexpr (SP2) {
;             PG8_LDB(B0, 0, 0); PG8_LDB(B1, 0, 1); PG8_SCHED; PG8_LDA(At, 0, 0); PG8_STAGE(PG8_SA(1, 1), a1 + hstep, voffA);
;             PG8_WAIT_V(8); PG8_WAIT_L(0); PG8_BAR; PG8_MMA(0, 0, At, B0); PG8_MMA(0, 1, At, B1); PG8_BAR; PG8_SCHED;
;             PG8_LDA(At, 0, 1); PG8_STAGE(PG8_SB(0, 0), b2, voffB); PG8_STAGE(PG8_SB(0, 1), b2 + hstep, voffB); PG8_STAGE(PG8_SA(0, 0), a2, voffA);
;             PG8_WAIT_V(8); PG8_WAIT_L(0); PG8_BAR; PG8_MMA(1, 0, At, B0); PG8_MMA(1, 1, At, B1); PG8_BAR; PG8_SCHED;
;             PG8_LDB(B0, 1, 0); PG8_LDB(B1, 1, 1); PG8_SCHED; PG8_LDA(At, 1, 0); PG8_STAGE(PG8_SA(0, 1), a2 + hstep, voffA);
;             PG8_WAIT_V(8); PG8_WAIT_L(0); PG8_BAR; PG8_MMA(0, 0, At, B0); PG8_MMA(0, 1, At, B1); PG8_BAR; PG8_SCHED;
;             PG8_LDA(At, 1, 1); PG8_STAGE(PG8_SB(1, 0), b3, voffB); PG8_STAGE(PG8_SB(1, 1), b3 + hstep, voffB); PG8_STAGE(PG8_SA(1, 0), a3, voffA);
;             PG8_WAIT_V(8); PG8_WAIT_L(0); PG8_BAR; PG8_MMA(1, 0, At, B0); PG8_MMA(1, 1, At, B1); PG8_BAR; PG8_SCHED;
.Lp1_rare0:
	s_cmp_eq_u32 s34, 0
	s_cbranch_scc1 .Lp1_kdone
	s_add_u32 s45, s16, 1
	s_and_b32 s40, s45, 1
	s_lshl_b32 s4, s40, 8
	s_sub_u32 s4, 128, s4
	s_sub_u32 s5, 0, s40
	s_mul_i32 s8, s40, 3968
	s_add_u32 s30, s26, s8
	s_addc_u32 s31, s27, 0
	s_add_u32 s32, s28, s8
	s_addc_u32 s33, s29, 0
	s_add_u32 s56, s30, 0x80000
	s_addc_u32 s57, s31, 0
	s_add_u32 s58, s32, 0x80000
	s_addc_u32 s59, s33, 0
	s_branch .Lp1_kloop0
.Lp1_kloop1:
	s_waitcnt vmcnt(8)
	s_waitcnt lgkmcnt(0)
	s_barrier
	v_mfma_f32_16x16x32_bf16 v[0:3], v[196:199], v[128:131], v[0:3]
	ds_read_b128 v[212:215], v247 offset:16384
	v_mfma_f32_16x16x32_bf16 v[0:3], v[200:203], v[132:135], v[0:3]
	ds_read_b128 v[216:219], v248 offset:16384
	v_mfma_f32_16x16x32_bf16 v[4:7], v[208:211], v[132:135], v[4:7]
	ds_read_b128 v[220:223], v247 offset:18432
	v_mfma_f32_16x16x32_bf16 v[4:7], v[204:207], v[128:131], v[4:7]
	ds_read_b128 v[224:227], v248 offset:18432
	v_mfma_f32_16x16x32_bf16 v[12:15], v[204:207], v[136:139], v[12:15]
	ds_read_b128 v[160:163], v245 offset:16384
	v_mfma_f32_16x16x32_bf16 v[12:15], v[208:211], v[140:143], v[12:15]
	ds_read_b128 v[164:167], v246 offset:16384
	v_mfma_f32_16x16x32_bf16 v[8:11], v[200:203], v[140:143], v[8:11]
	ds_read_b128 v[168:171], v245 offset:18432
	v_mfma_f32_16x16x32_bf16 v[8:11], v[196:199], v[136:139], v[8:11]
	ds_read_b128 v[172:175], v246 offset:18432
	v_mfma_f32_16x16x32_bf16 v[16:19], v[196:199], v[144:147], v[16:19]
	ds_read_b128 v[176:179], v245 offset:20480
	v_mfma_f32_16x16x32_bf16 v[16:19], v[200:203], v[148:151], v[16:19]
	ds_read_b128 v[180:183], v246 offset:20480
	v_mfma_f32_16x16x32_bf16 v[20:23], v[208:211], v[148:151], v[20:23]
	ds_read_b128 v[188:191], v245 offset:22528
	v_mfma_f32_16x16x32_bf16 v[20:23], v[204:207], v[144:147], v[20:23]
	ds_read_b128 v[192:195], v246 offset:22528
	v_mfma_f32_16x16x32_bf16 v[28:31], v[204:207], v[152:155], v[28:31]
	v_mfma_f32_16x16x32_bf16 v[28:31], v[208:211], v[156:159], v[28:31]
	v_mfma_f32_16x16x32_bf16 v[24:27], v[200:203], v[156:159], v[24:27]
	v_mfma_f32_16x16x32_bf16 v[24:27], v[196:199], v[152:155], v[24:27]
	s_waitcnt lgkmcnt(8)
	v_mfma_f32_16x16x32_bf16 v[32:35], v[212:215], v[128:131], v[32:35]
	v_mfma_f32_16x16x32_bf16 v[32:35], v[216:219], v[132:135], v[32:35]
	s_add_i32 m0, s35, 0x0
	v_mfma_f32_16x16x32_bf16 v[36:39], v[224:227], v[132:135], v[36:39]
	global_load_lds_dwordx4 v249, s[30:31]
	v_mfma_f32_16x16x32_bf16 v[36:39], v[220:223], v[128:131], v[36:39]
	v_mfma_f32_16x16x32_bf16 v[44:47], v[220:223], v[136:139], v[44:47]
	s_add_i32 m0, s35, 0x2000
	v_mfma_f32_16x16x32_bf16 v[44:47], v[224:227], v[140:143], v[44:47]
	global_load_lds_dwordx4 v250, s[30:31]
	v_mfma_f32_16x16x32_bf16 v[40:43], v[216:219], v[140:143], v[40:43]
	v_mfma_f32_16x16x32_bf16 v[40:43], v[212:215], v[136:139], v[40:43]
	s_add_i32 m0, s35, 0x10000
	v_mfma_f32_16x16x32_bf16 v[48:51], v[212:215], v[144:147], v[48:51]
	global_load_lds_dwordx4 v251, s[32:33]
	v_mfma_f32_16x16x32_bf16 v[48:51], v[216:219], v[148:151], v[48:51]
	v_mfma_f32_16x16x32_bf16 v[52:55], v[224:227], v[148:151], v[52:55]
	s_add_i32 m0, s35, 0x12000
	v_mfma_f32_16x16x32_bf16 v[52:55], v[220:223], v[144:147], v[52:55]
	global_load_lds_dwordx4 v252, s[32:33]
	v_mfma_f32_16x16x32_bf16 v[60:63], v[220:223], v[152:155], v[60:63]
	v_mfma_f32_16x16x32_bf16 v[60:63], v[224:227], v[156:159], v[60:63]
	v_mfma_f32_16x16x32_bf16 v[56:59], v[216:219], v[156:159], v[56:59]
	v_mfma_f32_16x16x32_bf16 v[56:59], v[212:215], v[152:155], v[56:59]
	s_waitcnt vmcnt(8)
	s_waitcnt lgkmcnt(0)
	s_barrier
	v_mfma_f32_16x16x32_bf16 v[96:99], v[212:215], v[160:163], v[96:99]
	ds_read_b128 v[128:131], v245 offset:32768
	v_mfma_f32_16x16x32_bf16 v[96:99], v[216:219], v[164:167], v[96:99]
	ds_read_b128 v[132:135], v246 offset:32768
	v_mfma_f32_16x16x32_bf16 v[100:103], v[224:227], v[164:167], v[100:103]
	ds_read_b128 v[136:139], v245 offset:34816
	v_mfma_f32_16x16x32_bf16 v[100:103], v[220:223], v[160:163], v[100:103]
	ds_read_b128 v[140:143], v246 offset:34816
	v_mfma_f32_16x16x32_bf16 v[108:111], v[220:223], v[168:171], v[108:111]
	ds_read_b128 v[144:147], v245 offset:36864
	v_mfma_f32_16x16x32_bf16 v[108:111], v[224:227], v[172:175], v[108:111]
	ds_read_b128 v[148:151], v246 offset:36864
	v_mfma_f32_16x16x32_bf16 v[104:107], v[216:219], v[172:175], v[104:107]
	ds_read_b128 v[152:155], v245 offset:38912
	v_mfma_f32_16x16x32_bf16 v[104:107], v[212:215], v[168:171], v[104:107]
	ds_read_b128 v[156:159], v246 offset:38912
	v_mfma_f32_16x16x32_bf16 v[112:115], v[212:215], v[176:179], v[112:115]
	v_mfma_f32_16x16x32_bf16 v[112:115], v[216:219], v[180:183], v[112:115]
	v_mfma_f32_16x16x32_bf16 v[116:119], v[224:227], v[180:183], v[116:119]
	v_mfma_f32_16x16x32_bf16 v[116:119], v[220:223], v[176:179], v[116:119]
	v_mfma_f32_16x16x32_bf16 v[124:127], v[220:223], v[188:191], v[124:127]
	v_mfma_f32_16x16x32_bf16 v[124:127], v[224:227], v[192:195], v[124:127]
	v_mfma_f32_16x16x32_bf16 v[120:123], v[216:219], v[192:195], v[120:123]
	v_mfma_f32_16x16x32_bf16 v[120:123], v[212:215], v[188:191], v[120:123]
	v_mfma_f32_16x16x32_bf16 v[64:67], v[196:199], v[160:163], v[64:67]
	ds_read_b128 v[212:215], v247 offset:49152
	v_mfma_f32_16x16x32_bf16 v[64:67], v[200:203], v[164:167], v[64:67]
	ds_read_b128 v[216:219], v248 offset:49152
	v_mfma_f32_16x16x32_bf16 v[68:71], v[208:211], v[164:167], v[68:71]
	ds_read_b128 v[220:223], v247 offset:51200
	v_mfma_f32_16x16x32_bf16 v[68:71], v[204:207], v[160:163], v[68:71]
	ds_read_b128 v[224:227], v248 offset:51200
	v_mfma_f32_16x16x32_bf16 v[76:79], v[204:207], v[168:171], v[76:79]
	s_add_i32 m0, s35, 0x4000
	v_mfma_f32_16x16x32_bf16 v[76:79], v[208:211], v[172:175], v[76:79]
	global_load_lds_dwordx4 v249, s[56:57]
	v_mfma_f32_16x16x32_bf16 v[72:75], v[200:203], v[172:175], v[72:75]
	s_add_i32 m0, s35, 0x6000
	v_mfma_f32_16x16x32_bf16 v[72:75], v[196:199], v[168:171], v[72:75]
	global_load_lds_dwordx4 v250, s[56:57]
	v_mfma_f32_16x16x32_bf16 v[80:83], v[196:199], v[176:179], v[80:83]
	s_add_i32 m0, s35, 0x14000
	v_mfma_f32_16x16x32_bf16 v[80:83], v[200:203], v[180:183], v[80:83]
	global_load_lds_dwordx4 v251, s[58:59]
	v_mfma_f32_16x16x32_bf16 v[84:87], v[208:211], v[180:183], v[84:87]
	s_add_i32 m0, s35, 0x16000
	v_mfma_f32_16x16x32_bf16 v[84:87], v[204:207], v[176:179], v[84:87]
	global_load_lds_dwordx4 v252, s[58:59]
	v_mfma_f32_16x16x32_bf16 v[92:95], v[204:207], v[188:191], v[92:95]
	s_add_u32 s30, s30, s4
	s_addc_u32 s31, s31, s5
	s_add_u32 s56, s56, s4
	s_addc_u32 s57, s57, s5
	v_mfma_f32_16x16x32_bf16 v[92:95], v[208:211], v[192:195], v[92:95]
	s_add_u32 s32, s32, s4
	s_addc_u32 s33, s33, s5
	s_add_u32 s58, s58, s4
	s_addc_u32 s59, s59, s5
	v_mfma_f32_16x16x32_bf16 v[88:91], v[200:203], v[192:195], v[88:91]
	v_mfma_f32_16x16x32_bf16 v[88:91], v[196:199], v[188:191], v[88:91]
	s_waitcnt vmcnt(8)
	s_waitcnt lgkmcnt(0)
	s_barrier
; #define PG8_STAGE(bufoff, gbase, voff) do { _Pragma("unroll") for (int _i = 0; _i < 2; ++_i) \
;         __builtin_amdgcn_global_load_lds((const unsigned*)((const char*)(gbase) + (voff)[_i]), (PG8_LAS unsigned*)(lds + (bufoff) + ldsw + _i * 8192), 16, 0, 0); } while (0)
; #define PG8_LDA(dst, b, h) do { _Pragma("unroll") for (int m = 0; m < 4; ++m) _Pragma("unroll") for (int k = 0; k < 2; ++k) dst[m][k] = *(const PG8_LAS bf16x8*)(lds + PG8_SA(b, h) + aoff + m * 2048 + k * 1024); } while (0)
; #define PG8_LDB(dst, b, h) do { _Pragma("unroll") for (int n = 0; n < 2; ++n) _Pragma("unroll") for (int k = 0; k < 2; ++k) dst[n][k] = *(const PG8_LAS bf16x8*)(lds + PG8_SB(b, h) + boff + n * 2048 + k * 1024); } while (0)
; #define PG8_MMA(ai, bj, At, Bt) do { __builtin_amdgcn_s_setprio(1); _Pragma("unroll") for (int m = 0; m < 4; ++m) _Pragma("unroll") for (int n = 0; n < 2; ++n) _Pragma("unroll") for (int k = 0; k < 2; ++k) \
;         acc[ai][bj][m][n] = __builtin_amdgcn_mfma_f32_16x16x32_bf16(Bt[n][k], At[m][k], acc[ai][bj][m][n], 0, 0, 0); __builtin_amdgcn_s_setprio(0); } while (0)
; #define PG8_WAIT_V(n) asm volatile("s_waitcnt vmcnt(" #n ")" ::: "memory")
; template <class Epi, class Sched, bool ALIGN_EPI = false, bool SP2 = false>
; __device__ __forceinline__ void gemm_phase(PG8_LAS unsigned char* lds, const Gemm g, const Sched& S, const Epi& E) {
;     ...
;             PG8_LDB(B0, 0, 0); PG8_LDB(B1, 0, 1); PG8_SCHED; PG8_LDA(At, 0, 0); PG8_STAGE(PG8_SA(1, 1), a1 + hstep, voffA);
;             PG8_WAIT_V(8); PG8_WAIT_L(0); PG8_BAR; PG8_MMA(0, 0, At, B0); PG8_MMA(0, 1, At, B1); PG8_BAR; PG8_SCHED;
;             PG8_LDA(At, 0, 1); PG8_STAGE(PG8_SB(0, 0), b2, voffB); PG8_STAGE(PG8_SB(0, 1), b2 + hstep, voffB); PG8_STAGE(PG8_SA(0, 0), a2, voffA);
;             PG8_WAIT_V(8); PG8_WAIT_L(0); PG8_BAR; PG8_MMA(1, 0, At, B0); PG8_MMA(1, 1, At, B1); PG8_BAR; PG8_SCHED;
;             PG8_LDB(B0, 1, 0); PG8_LDB(B1, 1, 1); PG8_SCHED; PG8_LDA(At, 1, 0); PG8_STAGE(PG8_SA(0, 1), a2 + hstep, voffA);
;             PG8_WAIT_V(8); PG8_WAIT_L(0); PG8_BAR; PG8_MMA(0, 0, At, B0); PG8_MMA(0, 1, At, B1); PG8_BAR; PG8_SCHED;
;             PG8_LDA(At, 1, 1); PG8_STAGE(PG8_SB(1, 0), b3, voffB); PG8_STAGE(PG8_SB(1, 1), b3 + hstep, voffB); PG8_STAGE(PG8_SA(1, 0), a3, voffA);
;             PG8_WAIT_V(8); PG8_WAIT_L(0); PG8_BAR; PG8_MMA(1, 0, At, B0); PG8_MMA(1, 1, At, B1); PG8_BAR; PG8_SCHED;
	v_mfma_f32_16x16x32_bf16 v[32:35], v[212:215], v[128:131], v[32:35]
	ds_read_b128 v[196:199], v247 offset:32768
	v_mfma_f32_16x16x32_bf16 v[32:35], v[216:219], v[132:135], v[32:35]
	ds_read_b128 v[200:203], v248 offset:32768
	v_mfma_f32_16x16x32_bf16 v[36:39], v[224:227], v[132:135], v[36:39]
	ds_read_b128 v[204:207], v247 offset:34816
	v_mfma_f32_16x16x32_bf16 v[36:39], v[220:223], v[128:131], v[36:39]
	ds_read_b128 v[208:211], v248 offset:34816
	v_mfma_f32_16x16x32_bf16 v[44:47], v[220:223], v[136:139], v[44:47]
	ds_read_b128 v[160:163], v245 offset:49152
	v_mfma_f32_16x16x32_bf16 v[44:47], v[224:227], v[140:143], v[44:47]
	ds_read_b128 v[164:167], v246 offset:49152
	v_mfma_f32_16x16x32_bf16 v[40:43], v[216:219], v[140:143], v[40:43]
	ds_read_b128 v[168:171], v245 offset:51200
	v_mfma_f32_16x16x32_bf16 v[40:43], v[212:215], v[136:139], v[40:43]
	ds_read_b128 v[172:175], v246 offset:51200
	v_mfma_f32_16x16x32_bf16 v[48:51], v[212:215], v[144:147], v[48:51]
	ds_read_b128 v[176:179], v245 offset:53248
	v_mfma_f32_16x16x32_bf16 v[48:51], v[216:219], v[148:151], v[48:51]
	ds_read_b128 v[180:183], v246 offset:53248
	v_mfma_f32_16x16x32_bf16 v[52:55], v[224:227], v[148:151], v[52:55]
	ds_read_b128 v[188:191], v245 offset:55296
	v_mfma_f32_16x16x32_bf16 v[52:55], v[220:223], v[144:147], v[52:55]
	ds_read_b128 v[192:195], v246 offset:55296
	v_mfma_f32_16x16x32_bf16 v[60:63], v[220:223], v[152:155], v[60:63]
	v_mfma_f32_16x16x32_bf16 v[60:63], v[224:227], v[156:159], v[60:63]
	v_mfma_f32_16x16x32_bf16 v[56:59], v[216:219], v[156:159], v[56:59]
	v_mfma_f32_16x16x32_bf16 v[56:59], v[212:215], v[152:155], v[56:59]
	s_waitcnt lgkmcnt(8)
	v_mfma_f32_16x16x32_bf16 v[0:3], v[196:199], v[128:131], v[0:3]
	v_mfma_f32_16x16x32_bf16 v[0:3], v[200:203], v[132:135], v[0:3]
	s_add_i32 m0, s35, 0x8000
	v_mfma_f32_16x16x32_bf16 v[4:7], v[208:211], v[132:135], v[4:7]
	global_load_lds_dwordx4 v249, s[30:31]
	v_mfma_f32_16x16x32_bf16 v[4:7], v[204:207], v[128:131], v[4:7]
	v_mfma_f32_16x16x32_bf16 v[12:15], v[204:207], v[136:139], v[12:15]
	s_add_i32 m0, s35, 0xa000
	v_mfma_f32_16x16x32_bf16 v[12:15], v[208:211], v[140:143], v[12:15]
	global_load_lds_dwordx4 v250, s[30:31]
	v_mfma_f32_16x16x32_bf16 v[8:11], v[200:203], v[140:143], v[8:11]
	v_mfma_f32_16x16x32_bf16 v[8:11], v[196:199], v[136:139], v[8:11]
	s_add_i32 m0, s35, 0x1c000
	v_mfma_f32_16x16x32_bf16 v[16:19], v[196:199], v[144:147], v[16:19]
	global_load_lds_dwordx4 v251, s[58:59]
	v_mfma_f32_16x16x32_bf16 v[16:19], v[200:203], v[148:151], v[16:19]
	v_mfma_f32_16x16x32_bf16 v[20:23], v[208:211], v[148:151], v[20:23]
	s_add_i32 m0, s35, 0x1e000
	v_mfma_f32_16x16x32_bf16 v[20:23], v[204:207], v[144:147], v[20:23]
	global_load_lds_dwordx4 v252, s[58:59]
	v_mfma_f32_16x16x32_bf16 v[28:31], v[204:207], v[152:155], v[28:31]
	v_mfma_f32_16x16x32_bf16 v[28:31], v[208:211], v[156:159], v[28:31]
	v_mfma_f32_16x16x32_bf16 v[24:27], v[200:203], v[156:159], v[24:27]
	v_mfma_f32_16x16x32_bf16 v[24:27], v[196:199], v[152:155], v[24:27]
	s_waitcnt vmcnt(8)
	s_waitcnt lgkmcnt(0)
	s_barrier
	v_mfma_f32_16x16x32_bf16 v[64:67], v[196:199], v[160:163], v[64:67]
	ds_read_b128 v[128:131], v245 offset:0
	v_mfma_f32_16x16x32_bf16 v[64:67], v[200:203], v[164:167], v[64:67]
	ds_read_b128 v[132:135], v246 offset:0
	v_mfma_f32_16x16x32_bf16 v[68:71], v[208:211], v[164:167], v[68:71]
	ds_read_b128 v[136:139], v245 offset:2048
	v_mfma_f32_16x16x32_bf16 v[68:71], v[204:207], v[160:163], v[68:71]
	ds_read_b128 v[140:143], v246 offset:2048
	v_mfma_f32_16x16x32_bf16 v[76:79], v[204:207], v[168:171], v[76:79]
	ds_read_b128 v[144:147], v245 offset:4096
	v_mfma_f32_16x16x32_bf16 v[76:79], v[208:211], v[172:175], v[76:79]
	ds_read_b128 v[148:151], v246 offset:4096
	v_mfma_f32_16x16x32_bf16 v[72:75], v[200:203], v[172:175], v[72:75]
	ds_read_b128 v[152:155], v245 offset:6144
	v_mfma_f32_16x16x32_bf16 v[72:75], v[196:199], v[168:171], v[72:75]
	ds_read_b128 v[156:159], v246 offset:6144
	v_mfma_f32_16x16x32_bf16 v[80:83], v[196:199], v[176:179], v[80:83]
	v_mfma_f32_16x16x32_bf16 v[80:83], v[200:203], v[180:183], v[80:83]
	v_mfma_f32_16x16x32_bf16 v[84:87], v[208:211], v[180:183], v[84:87]
	v_mfma_f32_16x16x32_bf16 v[84:87], v[204:207], v[176:179], v[84:87]
	v_mfma_f32_16x16x32_bf16 v[92:95], v[204:207], v[188:191], v[92:95]
	v_mfma_f32_16x16x32_bf16 v[92:95], v[208:211], v[192:195], v[92:95]
	v_mfma_f32_16x16x32_bf16 v[88:91], v[200:203], v[192:195], v[88:91]
	v_mfma_f32_16x16x32_bf16 v[88:91], v[196:199], v[188:191], v[88:91]
	v_mfma_f32_16x16x32_bf16 v[96:99], v[212:215], v[160:163], v[96:99]
	ds_read_b128 v[196:199], v247 offset:0
	v_mfma_f32_16x16x32_bf16 v[96:99], v[216:219], v[164:167], v[96:99]
	ds_read_b128 v[200:203], v248 offset:0
	v_mfma_f32_16x16x32_bf16 v[100:103], v[224:227], v[164:167], v[100:103]
	ds_read_b128 v[204:207], v247 offset:2048
	v_mfma_f32_16x16x32_bf16 v[100:103], v[220:223], v[160:163], v[100:103]
	ds_read_b128 v[208:211], v248 offset:2048
	v_mfma_f32_16x16x32_bf16 v[108:111], v[220:223], v[168:171], v[108:111]
	s_add_i32 m0, s35, 0xc000
	v_mfma_f32_16x16x32_bf16 v[108:111], v[224:227], v[172:175], v[108:111]
	global_load_lds_dwordx4 v249, s[56:57]
	v_mfma_f32_16x16x32_bf16 v[104:107], v[216:219], v[172:175], v[104:107]
	s_add_i32 m0, s35, 0xe000
	v_mfma_f32_16x16x32_bf16 v[104:107], v[212:215], v[168:171], v[104:107]
	global_load_lds_dwordx4 v250, s[56:57]
	v_mfma_f32_16x16x32_bf16 v[112:115], v[212:215], v[176:179], v[112:115]
	s_add_i32 m0, s35, 0x18000
	v_mfma_f32_16x16x32_bf16 v[112:115], v[216:219], v[180:183], v[112:115]
	global_load_lds_dwordx4 v251, s[32:33]
	v_mfma_f32_16x16x32_bf16 v[116:119], v[224:227], v[180:183], v[116:119]
	s_add_i32 m0, s35, 0x1a000
	v_mfma_f32_16x16x32_bf16 v[116:119], v[220:223], v[176:179], v[116:119]
	global_load_lds_dwordx4 v252, s[32:33]
	v_mfma_f32_16x16x32_bf16 v[124:127], v[220:223], v[188:191], v[124:127]
	s_add_u32 s30, s30, s4
	s_addc_u32 s31, s31, s5
	s_add_u32 s56, s56, s4
	s_addc_u32 s57, s57, s5
	v_mfma_f32_16x16x32_bf16 v[124:127], v[224:227], v[192:195], v[124:127]
	s_add_u32 s32, s32, s4
	s_addc_u32 s33, s33, s5
	s_add_u32 s58, s58, s4
	s_addc_u32 s59, s59, s5
	v_mfma_f32_16x16x32_bf16 v[120:123], v[216:219], v[192:195], v[120:123]
	s_add_i32 s34, s34, -1
	s_cmp_le_u32 s34, 1
	v_mfma_f32_16x16x32_bf16 v[120:123], v[212:215], v[188:191], v[120:123]
	s_cbranch_scc1 .Lp1_rare1
	s_branch .Lp1_kloop1

; template <class Epi, class Sched, bool ALIGN_EPI = false, bool SP2 = false>
; __device__ __forceinline__ void gemm_phase(PG8_LAS unsigned char* lds, const Gemm g, const Sched& S, const Epi& E) {
;     ...
;             const bool last = (t == nt - 2);
;             const char* a1 = cA + (size_t)(t + 1) * kstep;
;             const char* a2 = last ? nA : cA + (size_t)(t + 2) * kstep; const char* b2 = last ? nB : cB + (size_t)(t + 2) * kstep;
;             const char* a3 = a2 + kstep; const char* b3 = b2 + kstep;
;             if (last && has_next) S.a_ready(nxt);
.Lp6_rare0:
	s_cmp_eq_u32 s34, 0
	s_cbranch_scc1 .Lp6_kdone
	s_add_u32 s45, s16, 1
	s_and_b32 s40, s45, 1
	s_lshl_b32 s4, s40, 8
	s_sub_u32 s4, 128, s4
	s_sub_u32 s5, 0, s40
	s_mul_i32 s8, s40, 11136
	s_add_u32 s30, s26, s8
	s_addc_u32 s31, s27, 0
	s_add_u32 s32, s28, s8
	s_addc_u32 s33, s29, 0
	s_add_u32 s56, s30, 0x160000
	s_addc_u32 s57, s31, 0
	s_add_u32 s58, s32, 0x160000
	s_addc_u32 s59, s33, 0
	s_branch .Lp6_kloop0
